# attention K/V band staging: 12 row loads issued together instead of 9 serialized round trips (two loop instances)
# speedup vs baseline: 1.0269x; 1.0023x over previous
.LBB0_699:
	s_ashr_i32 s0, s82, 2
	v_readlane_b32 s1, v254, 33
	v_mov_b32_e32 v19, v172
	s_and_b32 s6, s0, s1
	v_readlane_b32 s1, v254, 25
	s_and_b32 s2, s82, 3
	s_ashr_i32 s0, s0, s1
	v_ashrrev_i32_e32 v16, 7, v19
	s_ashr_i32 s1, s0, 31
	v_readlane_b32 s3, v254, 11
	v_lshl_add_u32 v18, s2, 2, v16
	v_lshrrev_b32_e32 v16, 5, v19
	s_lshl_b64 s[0:1], s[0:1], s3
	v_and_b32_e32 v230, 2, v16
	s_lshl_b32 s5, s6, 7
	v_lshlrev_b32_e32 v16, 6, v18
	v_and_b32_e32 v229, 31, v19
	s_add_u32 s33, s0, s5
	v_ashrrev_i32_e32 v17, 31, v16
	v_bfe_u32 v26, v19, 5, 1
	s_addc_u32 s83, s1, 0
	v_lshlrev_b64 v[20:21], 1, v[16:17]
	v_lshl_or_b32 v27, v230, 5, v229
	v_lshl_add_u64 v[16:17], s[84:85], 0, v[20:21]
	v_lshlrev_b32_e32 v22, 4, v26
	v_mov_b32_e32 v23, v175
	v_or_b32_e32 v24, s33, v27
	v_mov_b32_e32 v25, s83
	v_lshl_add_u64 v[22:23], v[16:17], 0, v[22:23]
	v_lshl_add_u64 v[20:21], s[90:91], 0, v[20:21]
	v_lshlrev_b64 v[28:29], 11, v[24:25]
	v_or_b32_e32 v24, s5, v27
	v_or_b32_e32 v27, 32, v27
	v_lshlrev_b32_e32 v174, 3, v26
	v_lshl_add_u64 v[30:31], v[22:23], 0, v[28:29]
	v_lshlrev_b32_e32 v32, 4, v24
	v_mov_b32_e32 v33, v175
	v_lshl_add_u64 v[28:29], v[20:21], 0, v[28:29]
	v_or_b32_e32 v24, s33, v27
	v_lshl_add_u64 v[32:33], v[32:33], 2, s[88:89]
	v_lshl_add_u64 v[28:29], v[28:29], 0, v[174:175]
	v_lshlrev_b64 v[24:25], 11, v[24:25]
	v_or_b32_e32 v27, s5, v27
	global_load_dwordx4 v[92:95], v[32:33], off offset:48
	global_load_dwordx4 v[96:99], v[32:33], off offset:32
	global_load_dwordx4 v[100:103], v[32:33], off offset:16
	global_load_dwordx4 v[104:107], v[32:33], off
	global_load_dwordx4 v[108:111], v[30:31], off
	global_load_dwordx4 v[112:115], v[30:31], off offset:32
	global_load_dwordx4 v[116:119], v[30:31], off offset:64
	global_load_dwordx4 v[120:123], v[30:31], off offset:96
	global_load_dwordx2 v[184:185], v[28:29], off
	global_load_dwordx2 v[186:187], v[28:29], off offset:16
	global_load_dwordx2 v[188:189], v[28:29], off offset:32
	global_load_dwordx2 v[190:191], v[28:29], off offset:48
	global_load_dwordx2 v[192:193], v[28:29], off offset:64
	global_load_dwordx2 v[194:195], v[28:29], off offset:80
	global_load_dwordx2 v[196:197], v[28:29], off offset:96
	global_load_dwordx2 v[198:199], v[28:29], off offset:112
	v_lshlrev_b32_e32 v28, 4, v27
	v_mov_b32_e32 v29, v175
	v_lshl_add_u64 v[20:21], v[20:21], 0, v[24:25]
	v_lshl_add_u64 v[28:29], v[28:29], 2, s[88:89]
	v_lshl_add_u64 v[20:21], v[20:21], 0, v[174:175]
	v_lshl_add_u64 v[22:23], v[22:23], 0, v[24:25]
	global_load_dwordx4 v[124:127], v[28:29], off offset:48
	global_load_dwordx4 v[128:131], v[28:29], off offset:32
	global_load_dwordx4 v[132:135], v[28:29], off offset:16
	global_load_dwordx4 v[136:139], v[28:29], off
	global_load_dwordx4 v[140:143], v[22:23], off
	global_load_dwordx4 v[144:147], v[22:23], off offset:32
	global_load_dwordx4 v[148:151], v[22:23], off offset:64
	global_load_dwordx4 v[152:155], v[22:23], off offset:96
	global_load_dwordx2 v[200:201], v[20:21], off
	global_load_dwordx2 v[202:203], v[20:21], off offset:16
	global_load_dwordx2 v[204:205], v[20:21], off offset:32
	global_load_dwordx2 v[206:207], v[20:21], off offset:48
	global_load_dwordx2 v[208:209], v[20:21], off offset:64
	global_load_dwordx2 v[210:211], v[20:21], off offset:80
	global_load_dwordx2 v[212:213], v[20:21], off offset:96
	global_load_dwordx2 v[214:215], v[20:21], off offset:112
	s_addk_i32 s5, 0xff80
	v_and_b32_e32 v20, 7, v19
	v_ashrrev_i32_e32 v21, 3, v19
	s_lshl_b32 s4, s2, 6
	v_lshlrev_b32_e32 v22, 3, v20
	v_add_u32_e32 v24, s5, v21
	v_readlane_b32 s2, v254, 7
	v_lshl_add_u32 v20, v20, 4, 0
	v_lshlrev_b32_e32 v22, 1, v22
	v_readlane_b32 s100, v254, 7
	s_lshl_b32 s98, s4, 1
	s_mov_b32 s99, 0
	v_mov_b32_e32 v36, v22
	v_mov_b32_e32 v37, 0
	v_lshlrev_b32_e32 v38, 3, v19
	v_and_b32_e32 v38, 56, v38
	v_lshlrev_b32_e32 v38, 1, v38
	v_mov_b32_e32 v39, 0
	v_mov_b32_e32 v34, v19
	v_ashrrev_i32_e32 v34, 3, v34
	v_add_u32_e32 v34, s5, v34
	v_cmp_gt_u32_e32 vcc, s100, v34
	v_mov_b32_e32 v35, 0
	s_nop 0
	v_cndmask_b32_e32 v34, 0, v34, vcc
	v_lshl_add_u64 v[34:35], s[0:1], 0, v[34:35]
	v_lshlrev_b64 v[34:35], 9, v[34:35]
	v_lshl_add_u64 v[34:35], s[92:93], 0, v[34:35]
	v_lshl_add_u64 v[34:35], v[34:35], 0, s[98:99]
	v_lshl_add_u64 v[34:35], v[34:35], 0, v[36:37]
	global_load_dwordx4 v[40:43], v[34:35], off
	v_add_u32_e32 v34, 0x200, v19
	v_ashrrev_i32_e32 v34, 3, v34
	v_add_u32_e32 v34, s5, v34
	v_cmp_gt_u32_e32 vcc, s100, v34
	v_mov_b32_e32 v35, 0
	s_nop 0
	v_cndmask_b32_e32 v34, 0, v34, vcc
	v_lshl_add_u64 v[34:35], s[0:1], 0, v[34:35]
	v_lshlrev_b64 v[34:35], 9, v[34:35]
	v_lshl_add_u64 v[34:35], s[92:93], 0, v[34:35]
	v_lshl_add_u64 v[34:35], v[34:35], 0, s[98:99]
	v_lshl_add_u64 v[34:35], v[34:35], 0, v[36:37]
	global_load_dwordx4 v[44:47], v[34:35], off
	v_add_u32_e32 v34, 0x400, v19
	v_ashrrev_i32_e32 v34, 3, v34
	v_add_u32_e32 v34, s5, v34
	v_cmp_gt_u32_e32 vcc, s100, v34
	v_mov_b32_e32 v35, 0
	s_nop 0
	v_cndmask_b32_e32 v34, 0, v34, vcc
	v_lshl_add_u64 v[34:35], s[0:1], 0, v[34:35]
	v_lshlrev_b64 v[34:35], 9, v[34:35]
	v_lshl_add_u64 v[34:35], s[92:93], 0, v[34:35]
	v_lshl_add_u64 v[34:35], v[34:35], 0, s[98:99]
	v_lshl_add_u64 v[34:35], v[34:35], 0, v[36:37]
	global_load_dwordx4 v[48:51], v[34:35], off
	v_add_u32_e32 v34, 0x600, v19
	v_ashrrev_i32_e32 v34, 3, v34
	v_add_u32_e32 v34, s5, v34
	v_cmp_gt_u32_e32 vcc, s100, v34
	v_mov_b32_e32 v35, 0
	s_nop 0
	v_cndmask_b32_e32 v34, 0, v34, vcc
	v_lshl_add_u64 v[34:35], s[0:1], 0, v[34:35]
	v_lshlrev_b64 v[34:35], 9, v[34:35]
	v_lshl_add_u64 v[34:35], s[92:93], 0, v[34:35]
	v_lshl_add_u64 v[34:35], v[34:35], 0, s[98:99]
	v_lshl_add_u64 v[34:35], v[34:35], 0, v[36:37]
	global_load_dwordx4 v[52:55], v[34:35], off
	v_add_u32_e32 v34, 0x800, v19
	v_ashrrev_i32_e32 v34, 3, v34
	v_add_u32_e32 v34, s5, v34
	v_cmp_gt_u32_e32 vcc, s100, v34
	v_mov_b32_e32 v35, 0
	s_nop 0
	v_cndmask_b32_e32 v34, 0, v34, vcc
	v_lshl_add_u64 v[34:35], s[0:1], 0, v[34:35]
	v_lshlrev_b64 v[34:35], 9, v[34:35]
	v_lshl_add_u64 v[34:35], s[92:93], 0, v[34:35]
	v_lshl_add_u64 v[34:35], v[34:35], 0, s[98:99]
	v_lshl_add_u64 v[34:35], v[34:35], 0, v[36:37]
	global_load_dwordx4 v[56:59], v[34:35], off
	v_add_u32_e32 v34, 0xa00, v19
	v_ashrrev_i32_e32 v34, 3, v34
	v_add_u32_e32 v34, s5, v34
	v_cmp_gt_u32_e32 vcc, s100, v34
	v_mov_b32_e32 v35, 0
	s_nop 0
	v_cndmask_b32_e32 v34, 0, v34, vcc
	v_lshl_add_u64 v[34:35], s[0:1], 0, v[34:35]
	v_lshlrev_b64 v[34:35], 9, v[34:35]
	v_lshl_add_u64 v[34:35], s[92:93], 0, v[34:35]
	v_lshl_add_u64 v[34:35], v[34:35], 0, s[98:99]
	v_lshl_add_u64 v[34:35], v[34:35], 0, v[36:37]
	global_load_dwordx4 v[60:63], v[34:35], off
	v_mov_b32_e32 v34, v19
	v_ashrrev_i32_e32 v34, 2, v34
	v_and_b32_e32 v34, -2, v34
	v_add_u32_e32 v34, s5, v34
	v_cmp_gt_u32_e32 vcc, s100, v34
	v_mov_b32_e32 v35, 0
	s_nop 0
	v_cndmask_b32_e32 v34, 0, v34, vcc
	v_lshl_add_u64 v[34:35], s[0:1], 0, v[34:35]
	v_lshlrev_b64 v[34:35], 9, v[34:35]
	v_lshl_add_u64 v[34:35], s[94:95], 0, v[34:35]
	v_lshl_add_u64 v[34:35], v[34:35], 0, s[98:99]
	v_lshl_add_u64 v[34:35], v[34:35], 0, v[38:39]
	global_load_dwordx4 v[64:67], v[34:35], off
	global_load_dwordx4 v[68:71], v[34:35], off offset:512
	v_add_u32_e32 v34, 0x200, v19
	v_ashrrev_i32_e32 v34, 2, v34
	v_and_b32_e32 v34, -2, v34
	v_add_u32_e32 v34, s5, v34
	v_cmp_gt_u32_e32 vcc, s100, v34
	v_mov_b32_e32 v35, 0
	s_nop 0
	v_cndmask_b32_e32 v34, 0, v34, vcc
	v_lshl_add_u64 v[34:35], s[0:1], 0, v[34:35]
	v_lshlrev_b64 v[34:35], 9, v[34:35]
	v_lshl_add_u64 v[34:35], s[94:95], 0, v[34:35]
	v_lshl_add_u64 v[34:35], v[34:35], 0, s[98:99]
	v_lshl_add_u64 v[34:35], v[34:35], 0, v[38:39]
	global_load_dwordx4 v[72:75], v[34:35], off
	global_load_dwordx4 v[76:79], v[34:35], off offset:512
	v_add_u32_e32 v34, 0x400, v19
	v_ashrrev_i32_e32 v34, 2, v34
	v_and_b32_e32 v34, -2, v34
	v_add_u32_e32 v34, s5, v34
	v_cmp_gt_u32_e32 vcc, s100, v34
	v_mov_b32_e32 v35, 0
	s_nop 0
	v_cndmask_b32_e32 v34, 0, v34, vcc
	v_lshl_add_u64 v[34:35], s[0:1], 0, v[34:35]
	v_lshlrev_b64 v[34:35], 9, v[34:35]
	v_lshl_add_u64 v[34:35], s[94:95], 0, v[34:35]
	v_lshl_add_u64 v[34:35], v[34:35], 0, s[98:99]
	v_lshl_add_u64 v[34:35], v[34:35], 0, v[38:39]
	global_load_dwordx4 v[80:83], v[34:35], off
	global_load_dwordx4 v[84:87], v[34:35], off offset:512
	v_cmp_gt_u32_e32 vcc, s2, v24
	s_and_saveexec_b64 s[2:3], vcc
	s_cbranch_execz .LBB0_701
	v_mov_b32_e32 v25, v175
	v_lshl_add_u64 v[24:25], s[0:1], 0, v[24:25]
	v_lshlrev_b64 v[24:25], 9, v[24:25]
	v_readlane_b32 s12, v253, 3
	v_lshl_add_u64 v[24:25], s[92:93], 0, v[24:25]
	s_lshl_b32 s8, s4, 1
	s_mov_b32 s9, s12
	v_lshl_add_u64 v[24:25], v[24:25], 0, s[8:9]
	v_mov_b32_e32 v23, v175
	v_lshl_add_u64 v[24:25], v[24:25], 0, v[22:23]
	s_movk_i32 s7, 0x90
	v_mad_u64_u32 v[24:25], s[8:9], v21, s7, v[20:21]
	v_readlane_b32 s13, v253, 4
	v_readlane_b32 s14, v253, 5
	v_readlane_b32 s15, v253, 6
	v_readlane_b32 s16, v253, 7
	v_readlane_b32 s17, v253, 8
	v_readlane_b32 s18, v253, 9
	v_readlane_b32 s19, v253, 10
	v_readlane_b32 s20, v253, 11
	v_readlane_b32 s21, v253, 12
	v_readlane_b32 s22, v253, 13
	v_readlane_b32 s23, v253, 14
	v_readlane_b32 s24, v253, 15
	v_readlane_b32 s25, v253, 16
	v_readlane_b32 s26, v253, 17
	v_readlane_b32 s27, v253, 18
	s_waitcnt vmcnt(0)
	v_mov_b64_e32 v[28:29], v[40:41]
	v_mov_b64_e32 v[30:31], v[42:43]
	ds_write_b128 v24, v[28:31]
.LBB0_701:
	s_or_b64 exec, exec, s[2:3]
	v_add_u32_e32 v28, 0x200, v19
	v_ashrrev_i32_e32 v21, 3, v28
	v_add_u32_e32 v24, s5, v21
	v_readlane_b32 s2, v254, 7
	s_nop 1
	v_cmp_gt_u32_e32 vcc, s2, v24
	s_and_saveexec_b64 s[2:3], vcc
	s_cbranch_execz .LBB0_703
	v_mov_b32_e32 v25, v175
	v_lshl_add_u64 v[24:25], s[0:1], 0, v[24:25]
	v_lshlrev_b64 v[24:25], 9, v[24:25]
	v_readlane_b32 s12, v253, 3
	v_lshl_add_u64 v[24:25], s[92:93], 0, v[24:25]
	s_lshl_b32 s8, s4, 1
	s_mov_b32 s9, s12
	v_lshl_add_u64 v[24:25], v[24:25], 0, s[8:9]
	v_mov_b32_e32 v23, v175
	v_lshl_add_u64 v[24:25], v[24:25], 0, v[22:23]
	s_movk_i32 s7, 0x90
	v_mad_u64_u32 v[24:25], s[8:9], v21, s7, v[20:21]
	v_readlane_b32 s13, v253, 4
	v_readlane_b32 s14, v253, 5
	v_readlane_b32 s15, v253, 6
	v_readlane_b32 s16, v253, 7
	v_readlane_b32 s17, v253, 8
	v_readlane_b32 s18, v253, 9
	v_readlane_b32 s19, v253, 10
	v_readlane_b32 s20, v253, 11
	v_readlane_b32 s21, v253, 12
	v_readlane_b32 s22, v253, 13
	v_readlane_b32 s23, v253, 14
	v_readlane_b32 s24, v253, 15
	v_readlane_b32 s25, v253, 16
	v_readlane_b32 s26, v253, 17
	v_readlane_b32 s27, v253, 18
	s_waitcnt vmcnt(0)
	v_mov_b64_e32 v[30:31], v[44:45]
	v_mov_b64_e32 v[32:33], v[46:47]
	ds_write_b128 v24, v[30:33]
.LBB0_703:
	s_or_b64 exec, exec, s[2:3]
	v_add_u32_e32 v27, 0x400, v19
	v_ashrrev_i32_e32 v21, 3, v27
	v_add_u32_e32 v24, s5, v21
	v_readlane_b32 s2, v254, 7
	s_nop 1
	v_cmp_gt_u32_e32 vcc, s2, v24
	s_and_saveexec_b64 s[2:3], vcc
	s_cbranch_execz .LBB0_705
	v_mov_b32_e32 v25, v175
	v_lshl_add_u64 v[24:25], s[0:1], 0, v[24:25]
	v_lshlrev_b64 v[24:25], 9, v[24:25]
	v_readlane_b32 s12, v253, 3
	v_lshl_add_u64 v[24:25], s[92:93], 0, v[24:25]
	s_lshl_b32 s8, s4, 1
	s_mov_b32 s9, s12
	v_lshl_add_u64 v[24:25], v[24:25], 0, s[8:9]
	v_mov_b32_e32 v23, v175
	v_lshl_add_u64 v[24:25], v[24:25], 0, v[22:23]
	s_movk_i32 s7, 0x90
	v_mad_u64_u32 v[24:25], s[8:9], v21, s7, v[20:21]
	v_readlane_b32 s13, v253, 4
	v_readlane_b32 s14, v253, 5
	v_readlane_b32 s15, v253, 6
	v_readlane_b32 s16, v253, 7
	v_readlane_b32 s17, v253, 8
	v_readlane_b32 s18, v253, 9
	v_readlane_b32 s19, v253, 10
	v_readlane_b32 s20, v253, 11
	v_readlane_b32 s21, v253, 12
	v_readlane_b32 s22, v253, 13
	v_readlane_b32 s23, v253, 14
	v_readlane_b32 s24, v253, 15
	v_readlane_b32 s25, v253, 16
	v_readlane_b32 s26, v253, 17
	v_readlane_b32 s27, v253, 18
	s_waitcnt vmcnt(0)
	v_mov_b64_e32 v[30:31], v[48:49]
	v_mov_b64_e32 v[32:33], v[50:51]
	ds_write_b128 v24, v[30:33]
.LBB0_705:
	s_or_b64 exec, exec, s[2:3]
	v_add_u32_e32 v21, 0x600, v19
	v_ashrrev_i32_e32 v21, 3, v21
	v_add_u32_e32 v24, s5, v21
	v_readlane_b32 s2, v254, 7
	s_nop 1
	v_cmp_gt_u32_e32 vcc, s2, v24
	s_and_saveexec_b64 s[2:3], vcc
	s_cbranch_execz .LBB0_707
	v_mov_b32_e32 v25, v175
	v_lshl_add_u64 v[24:25], s[0:1], 0, v[24:25]
	v_lshlrev_b64 v[24:25], 9, v[24:25]
	v_readlane_b32 s12, v253, 3
	v_lshl_add_u64 v[24:25], s[92:93], 0, v[24:25]
	s_lshl_b32 s8, s4, 1
	s_mov_b32 s9, s12
	v_lshl_add_u64 v[24:25], v[24:25], 0, s[8:9]
	v_mov_b32_e32 v23, v175
	v_lshl_add_u64 v[24:25], v[24:25], 0, v[22:23]
	s_movk_i32 s7, 0x90
	v_mad_u64_u32 v[24:25], s[8:9], v21, s7, v[20:21]
	v_readlane_b32 s13, v253, 4
	v_readlane_b32 s14, v253, 5
	v_readlane_b32 s15, v253, 6
	v_readlane_b32 s16, v253, 7
	v_readlane_b32 s17, v253, 8
	v_readlane_b32 s18, v253, 9
	v_readlane_b32 s19, v253, 10
	v_readlane_b32 s20, v253, 11
	v_readlane_b32 s21, v253, 12
	v_readlane_b32 s22, v253, 13
	v_readlane_b32 s23, v253, 14
	v_readlane_b32 s24, v253, 15
	v_readlane_b32 s25, v253, 16
	v_readlane_b32 s26, v253, 17
	v_readlane_b32 s27, v253, 18
	s_waitcnt vmcnt(0)
	v_mov_b64_e32 v[30:31], v[52:53]
	v_mov_b64_e32 v[32:33], v[54:55]
	ds_write_b128 v24, v[30:33]
.LBB0_707:
	s_or_b64 exec, exec, s[2:3]
	v_add_u32_e32 v21, 0x800, v19
	v_ashrrev_i32_e32 v21, 3, v21
	v_add_u32_e32 v24, s5, v21
	v_readlane_b32 s2, v254, 7
	s_nop 1
	v_cmp_gt_u32_e32 vcc, s2, v24
	s_and_saveexec_b64 s[2:3], vcc
	s_cbranch_execz .LBB0_709
	v_mov_b32_e32 v25, v175
	v_lshl_add_u64 v[24:25], s[0:1], 0, v[24:25]
	v_lshlrev_b64 v[24:25], 9, v[24:25]
	v_readlane_b32 s12, v253, 3
	v_lshl_add_u64 v[24:25], s[92:93], 0, v[24:25]
	s_lshl_b32 s8, s4, 1
	s_mov_b32 s9, s12
	v_lshl_add_u64 v[24:25], v[24:25], 0, s[8:9]
	v_mov_b32_e32 v23, v175
	v_lshl_add_u64 v[24:25], v[24:25], 0, v[22:23]
	s_movk_i32 s7, 0x90
	v_mad_u64_u32 v[24:25], s[8:9], v21, s7, v[20:21]
	v_readlane_b32 s13, v253, 4
	v_readlane_b32 s14, v253, 5
	v_readlane_b32 s15, v253, 6
	v_readlane_b32 s16, v253, 7
	v_readlane_b32 s17, v253, 8
	v_readlane_b32 s18, v253, 9
	v_readlane_b32 s19, v253, 10
	v_readlane_b32 s20, v253, 11
	v_readlane_b32 s21, v253, 12
	v_readlane_b32 s22, v253, 13
	v_readlane_b32 s23, v253, 14
	v_readlane_b32 s24, v253, 15
	v_readlane_b32 s25, v253, 16
	v_readlane_b32 s26, v253, 17
	v_readlane_b32 s27, v253, 18
	s_waitcnt vmcnt(0)
	v_mov_b64_e32 v[30:31], v[56:57]
	v_mov_b64_e32 v[32:33], v[58:59]
	ds_write_b128 v24, v[30:33]
.LBB0_709:
	s_or_b64 exec, exec, s[2:3]
	v_add_u32_e32 v21, 0xa00, v19
	v_ashrrev_i32_e32 v21, 3, v21
	v_add_u32_e32 v24, s5, v21
	v_readlane_b32 s2, v254, 7
	s_nop 1
	v_cmp_gt_u32_e32 vcc, s2, v24
	s_and_saveexec_b64 s[2:3], vcc
	s_cbranch_execz .LBB0_711
	v_mov_b32_e32 v25, v175
	v_lshl_add_u64 v[24:25], s[0:1], 0, v[24:25]
	v_lshlrev_b64 v[24:25], 9, v[24:25]
	v_readlane_b32 s12, v253, 3
	v_lshl_add_u64 v[24:25], s[92:93], 0, v[24:25]
	s_lshl_b32 s8, s4, 1
	s_mov_b32 s9, s12
	v_lshl_add_u64 v[24:25], v[24:25], 0, s[8:9]
	v_mov_b32_e32 v23, v175
	v_lshl_add_u64 v[22:23], v[24:25], 0, v[22:23]
	s_movk_i32 s7, 0x90
	v_mad_u64_u32 v[20:21], s[8:9], v21, s7, v[20:21]
	v_readlane_b32 s13, v253, 4
	v_readlane_b32 s14, v253, 5
	v_readlane_b32 s15, v253, 6
	v_readlane_b32 s16, v253, 7
	v_readlane_b32 s17, v253, 8
	v_readlane_b32 s18, v253, 9
	v_readlane_b32 s19, v253, 10
	v_readlane_b32 s20, v253, 11
	v_readlane_b32 s21, v253, 12
	v_readlane_b32 s22, v253, 13
	v_readlane_b32 s23, v253, 14
	v_readlane_b32 s24, v253, 15
	v_readlane_b32 s25, v253, 16
	v_readlane_b32 s26, v253, 17
	v_readlane_b32 s27, v253, 18
	s_waitcnt vmcnt(0)
	v_mov_b64_e32 v[22:23], v[60:61]
	v_mov_b64_e32 v[24:25], v[62:63]
	ds_write_b128 v20, v[22:25]
.LBB0_711:
	s_or_b64 exec, exec, s[2:3]
	v_lshlrev_b32_e32 v20, 3, v19
	v_and_b32_e32 v21, 56, v20
	v_ashrrev_i32_e32 v20, 2, v19
	v_and_b32_e32 v25, -2, v20
	v_add_u32_e32 v22, s5, v25
	v_readlane_b32 s2, v254, 7
	v_lshlrev_b32_e32 v20, 1, v21
	v_mul_u32_u24_e32 v24, 0x308, v21
	v_cmp_gt_u32_e32 vcc, s2, v22
	s_and_saveexec_b64 s[2:3], vcc
	s_cbranch_execz .LBB0_713
	v_mov_b32_e32 v23, v175
	v_lshl_add_u64 v[22:23], s[0:1], 0, v[22:23]
	v_lshlrev_b64 v[22:23], 9, v[22:23]
	v_readlane_b32 s12, v253, 3
	v_lshl_add_u64 v[22:23], s[94:95], 0, v[22:23]
	s_lshl_b32 s8, s4, 1
	s_mov_b32 s9, s12
	v_lshl_add_u64 v[22:23], v[22:23], 0, s[8:9]
	v_mov_b32_e32 v21, v175
	v_lshl_add_u64 v[22:23], v[22:23], 0, v[20:21]
	v_lshlrev_b32_e32 v21, 1, v25
	v_add3_u32 v21, 0, v21, v24
	s_mov_b32 s7, 0xffff0000
	v_add_u32_e32 v25, 0xd800, v21
	v_readlane_b32 s13, v253, 4
	v_readlane_b32 s14, v253, 5
	v_readlane_b32 s15, v253, 6
	v_readlane_b32 s16, v253, 7
	v_readlane_b32 s17, v253, 8
	v_readlane_b32 s18, v253, 9
	v_readlane_b32 s19, v253, 10
	v_readlane_b32 s20, v253, 11
	v_readlane_b32 s21, v253, 12
	v_readlane_b32 s22, v253, 13
	v_readlane_b32 s23, v253, 14
	v_readlane_b32 s24, v253, 15
	v_readlane_b32 s25, v253, 16
	v_readlane_b32 s26, v253, 17
	v_readlane_b32 s27, v253, 18
	s_waitcnt vmcnt(0)
	v_mov_b64_e32 v[30:31], v[64:65]
	v_mov_b64_e32 v[32:33], v[66:67]
	v_mov_b64_e32 v[34:35], v[68:69]
	v_mov_b64_e32 v[36:37], v[70:71]
	v_and_b32_e32 v22, 0xffff, v30
	v_lshrrev_b32_e32 v23, 16, v30
	s_waitcnt vmcnt(0)
	v_lshl_or_b32 v22, v34, 16, v22
	v_and_or_b32 v23, v34, s7, v23
	ds_write2_b32 v25, v22, v23 offset1:194
	v_and_b32_e32 v22, 0xffff, v31
	v_lshrrev_b32_e32 v23, 16, v31
	v_lshl_or_b32 v22, v35, 16, v22
	v_and_or_b32 v23, v35, s7, v23
	v_add_u32_e32 v25, 0xde00, v21
	ds_write2_b32 v25, v22, v23 offset0:4 offset1:198
	v_and_b32_e32 v22, 0xffff, v32
	v_lshrrev_b32_e32 v23, 16, v32
	v_lshl_or_b32 v22, v36, 16, v22
	v_and_or_b32 v23, v36, s7, v23
	v_add_u32_e32 v25, 0xe400, v21
	ds_write2_b32 v25, v22, v23 offset0:8 offset1:202
	v_and_b32_e32 v22, 0xffff, v33
	v_lshrrev_b32_e32 v23, 16, v33
	v_lshl_or_b32 v22, v37, 16, v22
	v_and_or_b32 v23, v37, s7, v23
	v_add_u32_e32 v21, 0xea00, v21
	ds_write2_b32 v21, v22, v23 offset0:12 offset1:206
.LBB0_713:
	s_or_b64 exec, exec, s[2:3]
	v_ashrrev_i32_e32 v21, 2, v28
	v_and_b32_e32 v25, -2, v21
	v_add_u32_e32 v22, s5, v25
	v_readlane_b32 s2, v254, 7
	s_nop 1
	v_cmp_gt_u32_e32 vcc, s2, v22
	s_and_saveexec_b64 s[2:3], vcc
	s_cbranch_execz .LBB0_715
	v_mov_b32_e32 v23, v175
	v_lshl_add_u64 v[22:23], s[0:1], 0, v[22:23]
	v_lshlrev_b64 v[22:23], 9, v[22:23]
	v_readlane_b32 s12, v253, 3
	v_lshl_add_u64 v[22:23], s[94:95], 0, v[22:23]
	s_lshl_b32 s8, s4, 1
	s_mov_b32 s9, s12
	v_lshl_add_u64 v[22:23], v[22:23], 0, s[8:9]
	v_mov_b32_e32 v21, v175
	v_lshl_add_u64 v[22:23], v[22:23], 0, v[20:21]
	v_lshlrev_b32_e32 v21, 1, v25
	v_add3_u32 v21, 0, v21, v24
	s_mov_b32 s7, 0xffff0000
	v_add_u32_e32 v25, 0xd800, v21
	v_readlane_b32 s13, v253, 4
	v_readlane_b32 s14, v253, 5
	v_readlane_b32 s15, v253, 6
	v_readlane_b32 s16, v253, 7
	v_readlane_b32 s17, v253, 8
	v_readlane_b32 s18, v253, 9
	v_readlane_b32 s19, v253, 10
	v_readlane_b32 s20, v253, 11
	v_readlane_b32 s21, v253, 12
	v_readlane_b32 s22, v253, 13
	v_readlane_b32 s23, v253, 14
	v_readlane_b32 s24, v253, 15
	v_readlane_b32 s25, v253, 16
	v_readlane_b32 s26, v253, 17
	v_readlane_b32 s27, v253, 18
	s_waitcnt vmcnt(0)
	v_mov_b64_e32 v[28:29], v[72:73]
	v_mov_b64_e32 v[30:31], v[74:75]
	v_mov_b64_e32 v[32:33], v[76:77]
	v_mov_b64_e32 v[34:35], v[78:79]
	v_and_b32_e32 v22, 0xffff, v28
	v_lshrrev_b32_e32 v23, 16, v28
	s_waitcnt vmcnt(0)
	v_lshl_or_b32 v22, v32, 16, v22
	v_and_or_b32 v23, v32, s7, v23
	ds_write2_b32 v25, v22, v23 offset1:194
	v_and_b32_e32 v22, 0xffff, v29
	v_lshrrev_b32_e32 v23, 16, v29
	v_lshl_or_b32 v22, v33, 16, v22
	v_and_or_b32 v23, v33, s7, v23
	v_add_u32_e32 v25, 0xde00, v21
	ds_write2_b32 v25, v22, v23 offset0:4 offset1:198
	v_and_b32_e32 v22, 0xffff, v30
	v_lshrrev_b32_e32 v23, 16, v30
	v_lshl_or_b32 v22, v34, 16, v22
	v_and_or_b32 v23, v34, s7, v23
	v_add_u32_e32 v25, 0xe400, v21
	ds_write2_b32 v25, v22, v23 offset0:8 offset1:202
	v_and_b32_e32 v22, 0xffff, v31
	v_lshrrev_b32_e32 v23, 16, v31
	v_lshl_or_b32 v22, v35, 16, v22
	v_and_or_b32 v23, v35, s7, v23
	v_add_u32_e32 v21, 0xea00, v21
	ds_write2_b32 v21, v22, v23 offset0:12 offset1:206
.LBB0_715:
	s_or_b64 exec, exec, s[2:3]
	v_ashrrev_i32_e32 v21, 2, v27
	v_and_b32_e32 v25, -2, v21
	v_add_u32_e32 v22, s5, v25
	v_readlane_b32 s2, v254, 7
	s_nop 1
	v_cmp_gt_u32_e32 vcc, s2, v22
	s_and_saveexec_b64 s[2:3], vcc
	s_cbranch_execz .LBB0_717
	v_mov_b32_e32 v23, v175
	v_lshl_add_u64 v[22:23], s[0:1], 0, v[22:23]
	v_lshlrev_b64 v[22:23], 9, v[22:23]
	v_readlane_b32 s8, v253, 3
	v_lshl_add_u64 v[22:23], s[94:95], 0, v[22:23]
	s_lshl_b32 s0, s4, 1
	s_mov_b32 s1, s8
	v_lshl_add_u64 v[22:23], v[22:23], 0, s[0:1]
	v_mov_b32_e32 v21, v175
	v_lshl_add_u64 v[28:29], v[22:23], 0, v[20:21]
	s_nop 0
	v_lshlrev_b32_e32 v25, 1, v25
	v_add3_u32 v24, 0, v25, v24
	s_mov_b32 s0, 0xffff0000
	v_add_u32_e32 v25, 0xd800, v24
	v_readlane_b32 s9, v253, 4
	v_readlane_b32 s10, v253, 5
	v_readlane_b32 s11, v253, 6
	v_readlane_b32 s12, v253, 7
	v_readlane_b32 s13, v253, 8
	v_readlane_b32 s14, v253, 9
	v_readlane_b32 s15, v253, 10
	v_readlane_b32 s16, v253, 11
	v_readlane_b32 s17, v253, 12
	v_readlane_b32 s18, v253, 13
	v_readlane_b32 s19, v253, 14
	v_readlane_b32 s20, v253, 15
	v_readlane_b32 s21, v253, 16
	v_readlane_b32 s22, v253, 17
	v_readlane_b32 s23, v253, 18
	s_waitcnt vmcnt(0)
	v_mov_b64_e32 v[20:21], v[80:81]
	v_mov_b64_e32 v[22:23], v[82:83]
	v_mov_b64_e32 v[28:29], v[84:85]
	v_mov_b64_e32 v[30:31], v[86:87]
	v_and_b32_e32 v27, 0xffff, v20
	v_lshrrev_b32_e32 v20, 16, v20
	s_waitcnt vmcnt(0)
	v_lshl_or_b32 v27, v28, 16, v27
	v_and_or_b32 v20, v28, s0, v20
	ds_write2_b32 v25, v27, v20 offset1:194
	v_and_b32_e32 v20, 0xffff, v21
	v_lshrrev_b32_e32 v21, 16, v21
	v_lshl_or_b32 v20, v29, 16, v20
	v_and_or_b32 v21, v29, s0, v21
	v_add_u32_e32 v25, 0xde00, v24
	ds_write2_b32 v25, v20, v21 offset0:4 offset1:198
	v_and_b32_e32 v20, 0xffff, v22
	v_lshrrev_b32_e32 v21, 16, v22
	v_lshl_or_b32 v20, v30, 16, v20
	v_and_or_b32 v21, v30, s0, v21
	v_add_u32_e32 v22, 0xe400, v24
	ds_write2_b32 v22, v20, v21 offset0:8 offset1:202
	v_and_b32_e32 v20, 0xffff, v23
	v_lshrrev_b32_e32 v21, 16, v23
	v_lshl_or_b32 v20, v31, 16, v20
	v_and_or_b32 v21, v31, s0, v21
	v_add_u32_e32 v22, 0xea00, v24
	ds_write2_b32 v22, v20, v21 offset0:12 offset1:206

.LBB0_730:
	v_readlane_b32 s0, v253, 56
	s_lshl_b32 s0, s0, 2
	s_addk_i32 s0, 0xfe00
	s_add_i32 s0, s0, s76
	v_mov_b32_e32 v19, v172
	s_and_b32 s2, s0, 3
	s_ashr_i32 s0, s0, 2
	v_readlane_b32 s1, v254, 25
	s_and_b32 s6, s0, s92
	s_ashr_i32 s0, s0, s1
	v_ashrrev_i32_e32 v16, 7, v19
	s_ashr_i32 s1, s0, 31
	v_lshl_add_u32 v18, s2, 2, v16
	v_lshrrev_b32_e32 v16, 5, v19
	s_lshl_b64 s[0:1], s[0:1], 12
	v_and_b32_e32 v229, 2, v16
	s_lshl_b32 s5, s6, 7
	v_lshlrev_b32_e32 v16, 6, v18
	v_and_b32_e32 v228, 31, v19
	s_add_u32 s33, s0, s5
	v_ashrrev_i32_e32 v17, 31, v16
	v_bfe_u32 v26, v19, 5, 1
	s_addc_u32 s77, s1, 0
	v_lshlrev_b64 v[20:21], 1, v[16:17]
	v_lshl_or_b32 v27, v229, 5, v228
	v_lshl_add_u64 v[16:17], s[82:83], 0, v[20:21]
	v_lshlrev_b32_e32 v22, 4, v26
	v_mov_b32_e32 v23, v175
	v_or_b32_e32 v24, s33, v27
	v_mov_b32_e32 v25, s77
	v_lshl_add_u64 v[22:23], v[16:17], 0, v[22:23]
	v_lshl_add_u64 v[20:21], s[86:87], 0, v[20:21]
	v_lshlrev_b64 v[28:29], 11, v[24:25]
	v_or_b32_e32 v24, s5, v27
	v_or_b32_e32 v27, 32, v27
	v_lshlrev_b32_e32 v174, 3, v26
	v_lshl_add_u64 v[30:31], v[22:23], 0, v[28:29]
	v_lshlrev_b32_e32 v32, 4, v24
	v_mov_b32_e32 v33, v175
	v_lshl_add_u64 v[28:29], v[20:21], 0, v[28:29]
	v_or_b32_e32 v24, s33, v27
	v_lshl_add_u64 v[32:33], v[32:33], 2, s[84:85]
	v_lshl_add_u64 v[28:29], v[28:29], 0, v[174:175]
	v_lshlrev_b64 v[24:25], 11, v[24:25]
	v_or_b32_e32 v27, s5, v27
	global_load_dwordx4 v[92:95], v[32:33], off offset:48
	global_load_dwordx4 v[96:99], v[32:33], off offset:32
	global_load_dwordx4 v[100:103], v[32:33], off offset:16
	global_load_dwordx4 v[104:107], v[32:33], off
	global_load_dwordx4 v[108:111], v[30:31], off
	global_load_dwordx4 v[112:115], v[30:31], off offset:32
	global_load_dwordx4 v[116:119], v[30:31], off offset:64
	global_load_dwordx4 v[120:123], v[30:31], off offset:96
	global_load_dwordx2 v[184:185], v[28:29], off
	global_load_dwordx2 v[186:187], v[28:29], off offset:16
	global_load_dwordx2 v[188:189], v[28:29], off offset:32
	global_load_dwordx2 v[190:191], v[28:29], off offset:48
	global_load_dwordx2 v[192:193], v[28:29], off offset:64
	global_load_dwordx2 v[194:195], v[28:29], off offset:80
	global_load_dwordx2 v[196:197], v[28:29], off offset:96
	global_load_dwordx2 v[198:199], v[28:29], off offset:112
	v_lshlrev_b32_e32 v28, 4, v27
	v_mov_b32_e32 v29, v175
	v_lshl_add_u64 v[20:21], v[20:21], 0, v[24:25]
	v_lshl_add_u64 v[28:29], v[28:29], 2, s[84:85]
	v_lshl_add_u64 v[20:21], v[20:21], 0, v[174:175]
	v_lshl_add_u64 v[22:23], v[22:23], 0, v[24:25]
	global_load_dwordx4 v[124:127], v[28:29], off offset:48
	global_load_dwordx4 v[128:131], v[28:29], off offset:32
	global_load_dwordx4 v[132:135], v[28:29], off offset:16
	global_load_dwordx4 v[136:139], v[28:29], off
	global_load_dwordx4 v[140:143], v[22:23], off
	global_load_dwordx4 v[144:147], v[22:23], off offset:32
	global_load_dwordx4 v[148:151], v[22:23], off offset:64
	global_load_dwordx4 v[152:155], v[22:23], off offset:96
	global_load_dwordx2 v[200:201], v[20:21], off
	global_load_dwordx2 v[202:203], v[20:21], off offset:16
	global_load_dwordx2 v[204:205], v[20:21], off offset:32
	global_load_dwordx2 v[206:207], v[20:21], off offset:48
	global_load_dwordx2 v[208:209], v[20:21], off offset:64
	global_load_dwordx2 v[210:211], v[20:21], off offset:80
	global_load_dwordx2 v[212:213], v[20:21], off offset:96
	global_load_dwordx2 v[214:215], v[20:21], off offset:112
	s_addk_i32 s5, 0xff80
	v_and_b32_e32 v20, 7, v19
	v_ashrrev_i32_e32 v21, 3, v19
	s_lshl_b32 s4, s2, 6
	v_lshlrev_b32_e32 v22, 3, v20
	v_add_u32_e32 v24, s5, v21
	v_readlane_b32 s2, v254, 7
	v_lshl_add_u32 v20, v20, 4, 0
	v_lshlrev_b32_e32 v22, 1, v22
	v_readlane_b32 s100, v254, 7
	s_lshl_b32 s98, s4, 1
	s_mov_b32 s99, 0
	v_mov_b32_e32 v36, v22
	v_mov_b32_e32 v37, 0
	v_lshlrev_b32_e32 v38, 3, v19
	v_and_b32_e32 v38, 56, v38
	v_lshlrev_b32_e32 v38, 1, v38
	v_mov_b32_e32 v39, 0
	v_mov_b32_e32 v34, v19
	v_ashrrev_i32_e32 v34, 3, v34
	v_add_u32_e32 v34, s5, v34
	v_cmp_gt_u32_e32 vcc, s100, v34
	v_mov_b32_e32 v35, 0
	s_nop 0
	v_cndmask_b32_e32 v34, 0, v34, vcc
	v_lshl_add_u64 v[34:35], s[0:1], 0, v[34:35]
	v_lshlrev_b64 v[34:35], 9, v[34:35]
	v_lshl_add_u64 v[34:35], s[88:89], 0, v[34:35]
	v_lshl_add_u64 v[34:35], v[34:35], 0, s[98:99]
	v_lshl_add_u64 v[34:35], v[34:35], 0, v[36:37]
	global_load_dwordx4 v[40:43], v[34:35], off
	v_add_u32_e32 v34, 0x200, v19
	v_ashrrev_i32_e32 v34, 3, v34
	v_add_u32_e32 v34, s5, v34
	v_cmp_gt_u32_e32 vcc, s100, v34
	v_mov_b32_e32 v35, 0
	s_nop 0
	v_cndmask_b32_e32 v34, 0, v34, vcc
	v_lshl_add_u64 v[34:35], s[0:1], 0, v[34:35]
	v_lshlrev_b64 v[34:35], 9, v[34:35]
	v_lshl_add_u64 v[34:35], s[88:89], 0, v[34:35]
	v_lshl_add_u64 v[34:35], v[34:35], 0, s[98:99]
	v_lshl_add_u64 v[34:35], v[34:35], 0, v[36:37]
	global_load_dwordx4 v[44:47], v[34:35], off
	v_add_u32_e32 v34, 0x400, v19
	v_ashrrev_i32_e32 v34, 3, v34
	v_add_u32_e32 v34, s5, v34
	v_cmp_gt_u32_e32 vcc, s100, v34
	v_mov_b32_e32 v35, 0
	s_nop 0
	v_cndmask_b32_e32 v34, 0, v34, vcc
	v_lshl_add_u64 v[34:35], s[0:1], 0, v[34:35]
	v_lshlrev_b64 v[34:35], 9, v[34:35]
	v_lshl_add_u64 v[34:35], s[88:89], 0, v[34:35]
	v_lshl_add_u64 v[34:35], v[34:35], 0, s[98:99]
	v_lshl_add_u64 v[34:35], v[34:35], 0, v[36:37]
	global_load_dwordx4 v[48:51], v[34:35], off
	v_add_u32_e32 v34, 0x600, v19
	v_ashrrev_i32_e32 v34, 3, v34
	v_add_u32_e32 v34, s5, v34
	v_cmp_gt_u32_e32 vcc, s100, v34
	v_mov_b32_e32 v35, 0
	s_nop 0
	v_cndmask_b32_e32 v34, 0, v34, vcc
	v_lshl_add_u64 v[34:35], s[0:1], 0, v[34:35]
	v_lshlrev_b64 v[34:35], 9, v[34:35]
	v_lshl_add_u64 v[34:35], s[88:89], 0, v[34:35]
	v_lshl_add_u64 v[34:35], v[34:35], 0, s[98:99]
	v_lshl_add_u64 v[34:35], v[34:35], 0, v[36:37]
	global_load_dwordx4 v[52:55], v[34:35], off
	v_add_u32_e32 v34, 0x800, v19
	v_ashrrev_i32_e32 v34, 3, v34
	v_add_u32_e32 v34, s5, v34
	v_cmp_gt_u32_e32 vcc, s100, v34
	v_mov_b32_e32 v35, 0
	s_nop 0
	v_cndmask_b32_e32 v34, 0, v34, vcc
	v_lshl_add_u64 v[34:35], s[0:1], 0, v[34:35]
	v_lshlrev_b64 v[34:35], 9, v[34:35]
	v_lshl_add_u64 v[34:35], s[88:89], 0, v[34:35]
	v_lshl_add_u64 v[34:35], v[34:35], 0, s[98:99]
	v_lshl_add_u64 v[34:35], v[34:35], 0, v[36:37]
	global_load_dwordx4 v[56:59], v[34:35], off
	v_add_u32_e32 v34, 0xa00, v19
	v_ashrrev_i32_e32 v34, 3, v34
	v_add_u32_e32 v34, s5, v34
	v_cmp_gt_u32_e32 vcc, s100, v34
	v_mov_b32_e32 v35, 0
	s_nop 0
	v_cndmask_b32_e32 v34, 0, v34, vcc
	v_lshl_add_u64 v[34:35], s[0:1], 0, v[34:35]
	v_lshlrev_b64 v[34:35], 9, v[34:35]
	v_lshl_add_u64 v[34:35], s[88:89], 0, v[34:35]
	v_lshl_add_u64 v[34:35], v[34:35], 0, s[98:99]
	v_lshl_add_u64 v[34:35], v[34:35], 0, v[36:37]
	global_load_dwordx4 v[60:63], v[34:35], off
	v_mov_b32_e32 v34, v19
	v_ashrrev_i32_e32 v34, 2, v34
	v_and_b32_e32 v34, -2, v34
	v_add_u32_e32 v34, s5, v34
	v_cmp_gt_u32_e32 vcc, s100, v34
	v_mov_b32_e32 v35, 0
	s_nop 0
	v_cndmask_b32_e32 v34, 0, v34, vcc
	v_lshl_add_u64 v[34:35], s[0:1], 0, v[34:35]
	v_lshlrev_b64 v[34:35], 9, v[34:35]
	v_lshl_add_u64 v[34:35], s[90:91], 0, v[34:35]
	v_lshl_add_u64 v[34:35], v[34:35], 0, s[98:99]
	v_lshl_add_u64 v[34:35], v[34:35], 0, v[38:39]
	global_load_dwordx4 v[64:67], v[34:35], off
	global_load_dwordx4 v[68:71], v[34:35], off offset:512
	v_add_u32_e32 v34, 0x200, v19
	v_ashrrev_i32_e32 v34, 2, v34
	v_and_b32_e32 v34, -2, v34
	v_add_u32_e32 v34, s5, v34
	v_cmp_gt_u32_e32 vcc, s100, v34
	v_mov_b32_e32 v35, 0
	s_nop 0
	v_cndmask_b32_e32 v34, 0, v34, vcc
	v_lshl_add_u64 v[34:35], s[0:1], 0, v[34:35]
	v_lshlrev_b64 v[34:35], 9, v[34:35]
	v_lshl_add_u64 v[34:35], s[90:91], 0, v[34:35]
	v_lshl_add_u64 v[34:35], v[34:35], 0, s[98:99]
	v_lshl_add_u64 v[34:35], v[34:35], 0, v[38:39]
	global_load_dwordx4 v[72:75], v[34:35], off
	global_load_dwordx4 v[76:79], v[34:35], off offset:512
	v_add_u32_e32 v34, 0x400, v19
	v_ashrrev_i32_e32 v34, 2, v34
	v_and_b32_e32 v34, -2, v34
	v_add_u32_e32 v34, s5, v34
	v_cmp_gt_u32_e32 vcc, s100, v34
	v_mov_b32_e32 v35, 0
	s_nop 0
	v_cndmask_b32_e32 v34, 0, v34, vcc
	v_lshl_add_u64 v[34:35], s[0:1], 0, v[34:35]
	v_lshlrev_b64 v[34:35], 9, v[34:35]
	v_lshl_add_u64 v[34:35], s[90:91], 0, v[34:35]
	v_lshl_add_u64 v[34:35], v[34:35], 0, s[98:99]
	v_lshl_add_u64 v[34:35], v[34:35], 0, v[38:39]
	global_load_dwordx4 v[80:83], v[34:35], off
	global_load_dwordx4 v[84:87], v[34:35], off offset:512
	v_cmp_gt_u32_e32 vcc, s2, v24
	s_and_saveexec_b64 s[2:3], vcc
	s_cbranch_execz .LBB0_732
	v_mov_b32_e32 v25, v175
	v_lshl_add_u64 v[24:25], s[0:1], 0, v[24:25]
	v_lshlrev_b64 v[24:25], 9, v[24:25]
	v_readlane_b32 s12, v253, 3
	v_lshl_add_u64 v[24:25], s[88:89], 0, v[24:25]
	s_lshl_b32 s8, s4, 1
	s_mov_b32 s9, s12
	v_lshl_add_u64 v[24:25], v[24:25], 0, s[8:9]
	v_mov_b32_e32 v23, v175
	v_lshl_add_u64 v[24:25], v[24:25], 0, v[22:23]
	s_movk_i32 s7, 0x90
	v_mad_u64_u32 v[24:25], s[8:9], v21, s7, v[20:21]
	v_readlane_b32 s13, v253, 4
	v_readlane_b32 s14, v253, 5
	v_readlane_b32 s15, v253, 6
	v_readlane_b32 s16, v253, 7
	v_readlane_b32 s17, v253, 8
	v_readlane_b32 s18, v253, 9
	v_readlane_b32 s19, v253, 10
	v_readlane_b32 s20, v253, 11
	v_readlane_b32 s21, v253, 12
	v_readlane_b32 s22, v253, 13
	v_readlane_b32 s23, v253, 14
	v_readlane_b32 s24, v253, 15
	v_readlane_b32 s25, v253, 16
	v_readlane_b32 s26, v253, 17
	v_readlane_b32 s27, v253, 18
	s_waitcnt vmcnt(0)
	v_mov_b64_e32 v[28:29], v[40:41]
	v_mov_b64_e32 v[30:31], v[42:43]
	ds_write_b128 v24, v[28:31]
.LBB0_732:
	s_or_b64 exec, exec, s[2:3]
	v_add_u32_e32 v28, 0x200, v19
	v_ashrrev_i32_e32 v21, 3, v28
	v_add_u32_e32 v24, s5, v21
	v_readlane_b32 s2, v254, 7
	s_nop 1
	v_cmp_gt_u32_e32 vcc, s2, v24
	s_and_saveexec_b64 s[2:3], vcc
	s_cbranch_execz .LBB0_734
	v_mov_b32_e32 v25, v175
	v_lshl_add_u64 v[24:25], s[0:1], 0, v[24:25]
	v_lshlrev_b64 v[24:25], 9, v[24:25]
	v_readlane_b32 s12, v253, 3
	v_lshl_add_u64 v[24:25], s[88:89], 0, v[24:25]
	s_lshl_b32 s8, s4, 1
	s_mov_b32 s9, s12
	v_lshl_add_u64 v[24:25], v[24:25], 0, s[8:9]
	v_mov_b32_e32 v23, v175
	v_lshl_add_u64 v[24:25], v[24:25], 0, v[22:23]
	s_movk_i32 s7, 0x90
	v_mad_u64_u32 v[24:25], s[8:9], v21, s7, v[20:21]
	v_readlane_b32 s13, v253, 4
	v_readlane_b32 s14, v253, 5
	v_readlane_b32 s15, v253, 6
	v_readlane_b32 s16, v253, 7
	v_readlane_b32 s17, v253, 8
	v_readlane_b32 s18, v253, 9
	v_readlane_b32 s19, v253, 10
	v_readlane_b32 s20, v253, 11
	v_readlane_b32 s21, v253, 12
	v_readlane_b32 s22, v253, 13
	v_readlane_b32 s23, v253, 14
	v_readlane_b32 s24, v253, 15
	v_readlane_b32 s25, v253, 16
	v_readlane_b32 s26, v253, 17
	v_readlane_b32 s27, v253, 18
	s_waitcnt vmcnt(0)
	v_mov_b64_e32 v[30:31], v[44:45]
	v_mov_b64_e32 v[32:33], v[46:47]
	ds_write_b128 v24, v[30:33]
.LBB0_734:
	s_or_b64 exec, exec, s[2:3]
	v_add_u32_e32 v27, 0x400, v19
	v_ashrrev_i32_e32 v21, 3, v27
	v_add_u32_e32 v24, s5, v21
	v_readlane_b32 s2, v254, 7
	s_nop 1
	v_cmp_gt_u32_e32 vcc, s2, v24
	s_and_saveexec_b64 s[2:3], vcc
	s_cbranch_execz .LBB0_736
	v_mov_b32_e32 v25, v175
	v_lshl_add_u64 v[24:25], s[0:1], 0, v[24:25]
	v_lshlrev_b64 v[24:25], 9, v[24:25]
	v_readlane_b32 s12, v253, 3
	v_lshl_add_u64 v[24:25], s[88:89], 0, v[24:25]
	s_lshl_b32 s8, s4, 1
	s_mov_b32 s9, s12
	v_lshl_add_u64 v[24:25], v[24:25], 0, s[8:9]
	v_mov_b32_e32 v23, v175
	v_lshl_add_u64 v[24:25], v[24:25], 0, v[22:23]
	s_movk_i32 s7, 0x90
	v_mad_u64_u32 v[24:25], s[8:9], v21, s7, v[20:21]
	v_readlane_b32 s13, v253, 4
	v_readlane_b32 s14, v253, 5
	v_readlane_b32 s15, v253, 6
	v_readlane_b32 s16, v253, 7
	v_readlane_b32 s17, v253, 8
	v_readlane_b32 s18, v253, 9
	v_readlane_b32 s19, v253, 10
	v_readlane_b32 s20, v253, 11
	v_readlane_b32 s21, v253, 12
	v_readlane_b32 s22, v253, 13
	v_readlane_b32 s23, v253, 14
	v_readlane_b32 s24, v253, 15
	v_readlane_b32 s25, v253, 16
	v_readlane_b32 s26, v253, 17
	v_readlane_b32 s27, v253, 18
	s_waitcnt vmcnt(0)
	v_mov_b64_e32 v[30:31], v[48:49]
	v_mov_b64_e32 v[32:33], v[50:51]
	ds_write_b128 v24, v[30:33]
.LBB0_736:
	s_or_b64 exec, exec, s[2:3]
	v_add_u32_e32 v21, 0x600, v19
	v_ashrrev_i32_e32 v21, 3, v21
	v_add_u32_e32 v24, s5, v21
	v_readlane_b32 s2, v254, 7
	s_nop 1
	v_cmp_gt_u32_e32 vcc, s2, v24
	s_and_saveexec_b64 s[2:3], vcc
	s_cbranch_execz .LBB0_738
	v_mov_b32_e32 v25, v175
	v_lshl_add_u64 v[24:25], s[0:1], 0, v[24:25]
	v_lshlrev_b64 v[24:25], 9, v[24:25]
	v_readlane_b32 s12, v253, 3
	v_lshl_add_u64 v[24:25], s[88:89], 0, v[24:25]
	s_lshl_b32 s8, s4, 1
	s_mov_b32 s9, s12
	v_lshl_add_u64 v[24:25], v[24:25], 0, s[8:9]
	v_mov_b32_e32 v23, v175
	v_lshl_add_u64 v[24:25], v[24:25], 0, v[22:23]
	s_movk_i32 s7, 0x90
	v_mad_u64_u32 v[24:25], s[8:9], v21, s7, v[20:21]
	v_readlane_b32 s13, v253, 4
	v_readlane_b32 s14, v253, 5
	v_readlane_b32 s15, v253, 6
	v_readlane_b32 s16, v253, 7
	v_readlane_b32 s17, v253, 8
	v_readlane_b32 s18, v253, 9
	v_readlane_b32 s19, v253, 10
	v_readlane_b32 s20, v253, 11
	v_readlane_b32 s21, v253, 12
	v_readlane_b32 s22, v253, 13
	v_readlane_b32 s23, v253, 14
	v_readlane_b32 s24, v253, 15
	v_readlane_b32 s25, v253, 16
	v_readlane_b32 s26, v253, 17
	v_readlane_b32 s27, v253, 18
	s_waitcnt vmcnt(0)
	v_mov_b64_e32 v[30:31], v[52:53]
	v_mov_b64_e32 v[32:33], v[54:55]
	ds_write_b128 v24, v[30:33]
.LBB0_738:
	s_or_b64 exec, exec, s[2:3]
	v_add_u32_e32 v21, 0x800, v19
	v_ashrrev_i32_e32 v21, 3, v21
	v_add_u32_e32 v24, s5, v21
	v_readlane_b32 s2, v254, 7
	s_nop 1
	v_cmp_gt_u32_e32 vcc, s2, v24
	s_and_saveexec_b64 s[2:3], vcc
	s_cbranch_execz .LBB0_740
	v_mov_b32_e32 v25, v175
	v_lshl_add_u64 v[24:25], s[0:1], 0, v[24:25]
	v_lshlrev_b64 v[24:25], 9, v[24:25]
	v_readlane_b32 s12, v253, 3
	v_lshl_add_u64 v[24:25], s[88:89], 0, v[24:25]
	s_lshl_b32 s8, s4, 1
	s_mov_b32 s9, s12
	v_lshl_add_u64 v[24:25], v[24:25], 0, s[8:9]
	v_mov_b32_e32 v23, v175
	v_lshl_add_u64 v[24:25], v[24:25], 0, v[22:23]
	s_movk_i32 s7, 0x90
	v_mad_u64_u32 v[24:25], s[8:9], v21, s7, v[20:21]
	v_readlane_b32 s13, v253, 4
	v_readlane_b32 s14, v253, 5
	v_readlane_b32 s15, v253, 6
	v_readlane_b32 s16, v253, 7
	v_readlane_b32 s17, v253, 8
	v_readlane_b32 s18, v253, 9
	v_readlane_b32 s19, v253, 10
	v_readlane_b32 s20, v253, 11
	v_readlane_b32 s21, v253, 12
	v_readlane_b32 s22, v253, 13
	v_readlane_b32 s23, v253, 14
	v_readlane_b32 s24, v253, 15
	v_readlane_b32 s25, v253, 16
	v_readlane_b32 s26, v253, 17
	v_readlane_b32 s27, v253, 18
	s_waitcnt vmcnt(0)
	v_mov_b64_e32 v[30:31], v[56:57]
	v_mov_b64_e32 v[32:33], v[58:59]
	ds_write_b128 v24, v[30:33]
.LBB0_740:
	s_or_b64 exec, exec, s[2:3]
	v_add_u32_e32 v21, 0xa00, v19
	v_ashrrev_i32_e32 v21, 3, v21
	v_add_u32_e32 v24, s5, v21
	v_readlane_b32 s2, v254, 7
	s_nop 1
	v_cmp_gt_u32_e32 vcc, s2, v24
	s_and_saveexec_b64 s[2:3], vcc
	s_cbranch_execz .LBB0_742
	v_mov_b32_e32 v25, v175
	v_lshl_add_u64 v[24:25], s[0:1], 0, v[24:25]
	v_lshlrev_b64 v[24:25], 9, v[24:25]
	v_readlane_b32 s12, v253, 3
	v_lshl_add_u64 v[24:25], s[88:89], 0, v[24:25]
	s_lshl_b32 s8, s4, 1
	s_mov_b32 s9, s12
	v_lshl_add_u64 v[24:25], v[24:25], 0, s[8:9]
	v_mov_b32_e32 v23, v175
	v_lshl_add_u64 v[22:23], v[24:25], 0, v[22:23]
	s_movk_i32 s7, 0x90
	v_mad_u64_u32 v[20:21], s[8:9], v21, s7, v[20:21]
	v_readlane_b32 s13, v253, 4
	v_readlane_b32 s14, v253, 5
	v_readlane_b32 s15, v253, 6
	v_readlane_b32 s16, v253, 7
	v_readlane_b32 s17, v253, 8
	v_readlane_b32 s18, v253, 9
	v_readlane_b32 s19, v253, 10
	v_readlane_b32 s20, v253, 11
	v_readlane_b32 s21, v253, 12
	v_readlane_b32 s22, v253, 13
	v_readlane_b32 s23, v253, 14
	v_readlane_b32 s24, v253, 15
	v_readlane_b32 s25, v253, 16
	v_readlane_b32 s26, v253, 17
	v_readlane_b32 s27, v253, 18
	s_waitcnt vmcnt(0)
	v_mov_b64_e32 v[22:23], v[60:61]
	v_mov_b64_e32 v[24:25], v[62:63]
	ds_write_b128 v20, v[22:25]
.LBB0_742:
	s_or_b64 exec, exec, s[2:3]
	v_lshlrev_b32_e32 v20, 3, v19
	v_and_b32_e32 v21, 56, v20
	v_ashrrev_i32_e32 v20, 2, v19
	v_and_b32_e32 v25, -2, v20
	v_add_u32_e32 v22, s5, v25
	v_readlane_b32 s2, v254, 7
	v_lshlrev_b32_e32 v20, 1, v21
	v_mul_u32_u24_e32 v24, 0x308, v21
	v_cmp_gt_u32_e32 vcc, s2, v22
	s_and_saveexec_b64 s[2:3], vcc
	s_cbranch_execz .LBB0_744
	v_mov_b32_e32 v23, v175
	v_lshl_add_u64 v[22:23], s[0:1], 0, v[22:23]
	v_lshlrev_b64 v[22:23], 9, v[22:23]
	v_readlane_b32 s12, v253, 3
	v_lshl_add_u64 v[22:23], s[90:91], 0, v[22:23]
	s_lshl_b32 s8, s4, 1
	s_mov_b32 s9, s12
	v_lshl_add_u64 v[22:23], v[22:23], 0, s[8:9]
	v_mov_b32_e32 v21, v175
	v_lshl_add_u64 v[22:23], v[22:23], 0, v[20:21]
	v_lshlrev_b32_e32 v21, 1, v25
	v_add3_u32 v21, 0, v21, v24
	s_mov_b32 s7, 0xffff0000
	v_add_u32_e32 v25, 0xd800, v21
	v_readlane_b32 s13, v253, 4
	v_readlane_b32 s14, v253, 5
	v_readlane_b32 s15, v253, 6
	v_readlane_b32 s16, v253, 7
	v_readlane_b32 s17, v253, 8
	v_readlane_b32 s18, v253, 9
	v_readlane_b32 s19, v253, 10
	v_readlane_b32 s20, v253, 11
	v_readlane_b32 s21, v253, 12
	v_readlane_b32 s22, v253, 13
	v_readlane_b32 s23, v253, 14
	v_readlane_b32 s24, v253, 15
	v_readlane_b32 s25, v253, 16
	v_readlane_b32 s26, v253, 17
	v_readlane_b32 s27, v253, 18
	s_waitcnt vmcnt(0)
	v_mov_b64_e32 v[30:31], v[64:65]
	v_mov_b64_e32 v[32:33], v[66:67]
	v_mov_b64_e32 v[34:35], v[68:69]
	v_mov_b64_e32 v[36:37], v[70:71]
	v_and_b32_e32 v22, 0xffff, v30
	v_lshrrev_b32_e32 v23, 16, v30
	s_waitcnt vmcnt(0)
	v_lshl_or_b32 v22, v34, 16, v22
	v_and_or_b32 v23, v34, s7, v23
	ds_write2_b32 v25, v22, v23 offset1:194
	v_and_b32_e32 v22, 0xffff, v31
	v_lshrrev_b32_e32 v23, 16, v31
	v_lshl_or_b32 v22, v35, 16, v22
	v_and_or_b32 v23, v35, s7, v23
	v_add_u32_e32 v25, 0xde00, v21
	ds_write2_b32 v25, v22, v23 offset0:4 offset1:198
	v_and_b32_e32 v22, 0xffff, v32
	v_lshrrev_b32_e32 v23, 16, v32
	v_lshl_or_b32 v22, v36, 16, v22
	v_and_or_b32 v23, v36, s7, v23
	v_add_u32_e32 v25, 0xe400, v21
	ds_write2_b32 v25, v22, v23 offset0:8 offset1:202
	v_and_b32_e32 v22, 0xffff, v33
	v_lshrrev_b32_e32 v23, 16, v33
	v_lshl_or_b32 v22, v37, 16, v22
	v_and_or_b32 v23, v37, s7, v23
	v_add_u32_e32 v21, 0xea00, v21
	ds_write2_b32 v21, v22, v23 offset0:12 offset1:206
.LBB0_744:
	s_or_b64 exec, exec, s[2:3]
	v_ashrrev_i32_e32 v21, 2, v28
	v_and_b32_e32 v25, -2, v21
	v_add_u32_e32 v22, s5, v25
	v_readlane_b32 s2, v254, 7
	s_nop 1
	v_cmp_gt_u32_e32 vcc, s2, v22
	s_and_saveexec_b64 s[2:3], vcc
	s_cbranch_execz .LBB0_746
	v_mov_b32_e32 v23, v175
	v_lshl_add_u64 v[22:23], s[0:1], 0, v[22:23]
	v_lshlrev_b64 v[22:23], 9, v[22:23]
	v_readlane_b32 s12, v253, 3
	v_lshl_add_u64 v[22:23], s[90:91], 0, v[22:23]
	s_lshl_b32 s8, s4, 1
	s_mov_b32 s9, s12
	v_lshl_add_u64 v[22:23], v[22:23], 0, s[8:9]
	v_mov_b32_e32 v21, v175
	v_lshl_add_u64 v[22:23], v[22:23], 0, v[20:21]
	v_lshlrev_b32_e32 v21, 1, v25
	v_add3_u32 v21, 0, v21, v24
	s_mov_b32 s7, 0xffff0000
	v_add_u32_e32 v25, 0xd800, v21
	v_readlane_b32 s13, v253, 4
	v_readlane_b32 s14, v253, 5
	v_readlane_b32 s15, v253, 6
	v_readlane_b32 s16, v253, 7
	v_readlane_b32 s17, v253, 8
	v_readlane_b32 s18, v253, 9
	v_readlane_b32 s19, v253, 10
	v_readlane_b32 s20, v253, 11
	v_readlane_b32 s21, v253, 12
	v_readlane_b32 s22, v253, 13
	v_readlane_b32 s23, v253, 14
	v_readlane_b32 s24, v253, 15
	v_readlane_b32 s25, v253, 16
	v_readlane_b32 s26, v253, 17
	v_readlane_b32 s27, v253, 18
	s_waitcnt vmcnt(0)
	v_mov_b64_e32 v[28:29], v[72:73]
	v_mov_b64_e32 v[30:31], v[74:75]
	v_mov_b64_e32 v[32:33], v[76:77]
	v_mov_b64_e32 v[34:35], v[78:79]
	v_and_b32_e32 v22, 0xffff, v28
	v_lshrrev_b32_e32 v23, 16, v28
	s_waitcnt vmcnt(0)
	v_lshl_or_b32 v22, v32, 16, v22
	v_and_or_b32 v23, v32, s7, v23
	ds_write2_b32 v25, v22, v23 offset1:194
	v_and_b32_e32 v22, 0xffff, v29
	v_lshrrev_b32_e32 v23, 16, v29
	v_lshl_or_b32 v22, v33, 16, v22
	v_and_or_b32 v23, v33, s7, v23
	v_add_u32_e32 v25, 0xde00, v21
	ds_write2_b32 v25, v22, v23 offset0:4 offset1:198
	v_and_b32_e32 v22, 0xffff, v30
	v_lshrrev_b32_e32 v23, 16, v30
	v_lshl_or_b32 v22, v34, 16, v22
	v_and_or_b32 v23, v34, s7, v23
	v_add_u32_e32 v25, 0xe400, v21
	ds_write2_b32 v25, v22, v23 offset0:8 offset1:202
	v_and_b32_e32 v22, 0xffff, v31
	v_lshrrev_b32_e32 v23, 16, v31
	v_lshl_or_b32 v22, v35, 16, v22
	v_and_or_b32 v23, v35, s7, v23
	v_add_u32_e32 v21, 0xea00, v21
	ds_write2_b32 v21, v22, v23 offset0:12 offset1:206
.LBB0_746:
	s_or_b64 exec, exec, s[2:3]
	v_ashrrev_i32_e32 v21, 2, v27
	v_and_b32_e32 v25, -2, v21
	v_add_u32_e32 v22, s5, v25
	v_readlane_b32 s2, v254, 7
	s_nop 1
	v_cmp_gt_u32_e32 vcc, s2, v22
	s_and_saveexec_b64 s[2:3], vcc
	s_cbranch_execz .LBB0_748
	v_mov_b32_e32 v23, v175
	v_lshl_add_u64 v[22:23], s[0:1], 0, v[22:23]
	v_lshlrev_b64 v[22:23], 9, v[22:23]
	v_readlane_b32 s8, v253, 3
	v_lshl_add_u64 v[22:23], s[90:91], 0, v[22:23]
	s_lshl_b32 s0, s4, 1
	s_mov_b32 s1, s8
	v_lshl_add_u64 v[22:23], v[22:23], 0, s[0:1]
	v_mov_b32_e32 v21, v175
	v_lshl_add_u64 v[28:29], v[22:23], 0, v[20:21]
	s_nop 0
	v_lshlrev_b32_e32 v25, 1, v25
	v_add3_u32 v24, 0, v25, v24
	s_mov_b32 s0, 0xffff0000
	v_add_u32_e32 v25, 0xd800, v24
	v_readlane_b32 s9, v253, 4
	v_readlane_b32 s10, v253, 5
	v_readlane_b32 s11, v253, 6
	v_readlane_b32 s12, v253, 7
	v_readlane_b32 s13, v253, 8
	v_readlane_b32 s14, v253, 9
	v_readlane_b32 s15, v253, 10
	v_readlane_b32 s16, v253, 11
	v_readlane_b32 s17, v253, 12
	v_readlane_b32 s18, v253, 13
	v_readlane_b32 s19, v253, 14
	v_readlane_b32 s20, v253, 15
	v_readlane_b32 s21, v253, 16
	v_readlane_b32 s22, v253, 17
	v_readlane_b32 s23, v253, 18
	s_waitcnt vmcnt(0)
	v_mov_b64_e32 v[20:21], v[80:81]
	v_mov_b64_e32 v[22:23], v[82:83]
	v_mov_b64_e32 v[28:29], v[84:85]
	v_mov_b64_e32 v[30:31], v[86:87]
	v_and_b32_e32 v27, 0xffff, v20
	v_lshrrev_b32_e32 v20, 16, v20
	s_waitcnt vmcnt(0)
	v_lshl_or_b32 v27, v28, 16, v27
	v_and_or_b32 v20, v28, s0, v20
	ds_write2_b32 v25, v27, v20 offset1:194
	v_and_b32_e32 v20, 0xffff, v21
	v_lshrrev_b32_e32 v21, 16, v21
	v_lshl_or_b32 v20, v29, 16, v20
	v_and_or_b32 v21, v29, s0, v21
	v_add_u32_e32 v25, 0xde00, v24
	ds_write2_b32 v25, v20, v21 offset0:4 offset1:198
	v_and_b32_e32 v20, 0xffff, v22
	v_lshrrev_b32_e32 v21, 16, v22
	v_lshl_or_b32 v20, v30, 16, v20
	v_and_or_b32 v21, v30, s0, v21
	v_add_u32_e32 v22, 0xe400, v24
	ds_write2_b32 v22, v20, v21 offset0:8 offset1:202
	v_and_b32_e32 v20, 0xffff, v23
	v_lshrrev_b32_e32 v21, 16, v23
	v_lshl_or_b32 v20, v31, 16, v20
	v_and_or_b32 v21, v31, s0, v21
	v_add_u32_e32 v22, 0xea00, v24
	ds_write2_b32 v22, v20, v21 offset0:12 offset1:206
